# GELU in-projection K-loop: first iteration peeled, MFMAs that read an initial accumulator take C=0 (also where D differs from C), 128 zeroing v_mov per tile removed
# baseline (speedup 1.0000x reference)
; #define PG8_STAGE(bufoff, gbase, voff) do { _Pragma("unroll") for (int _i = 0; _i < 2; ++_i) { \
;         const unsigned _m0 = ldsb + (unsigned)((bufoff) + _i * 8192); const char* _gb = (const char*)(gbase); \
;         asm volatile("s_mov_b32 m0, %0\n\ts_nop 0\n\tglobal_load_lds_dwordx4 %1, %2" :: "s"(_m0), "v"((voff)[_i]), "s"(_gb) : "m0", "memory"); } } while (0)
; #define PG8_LDA(dst, b, h) do { _Pragma("unroll") for (int m = 0; m < 4; ++m) _Pragma("unroll") for (int k = 0; k < 2; ++k) dst[m][k] = *(const LAS bf16x8*)(lds + PG8_SA(b, h) + aoff + m * 2048 + k * 1024); } while (0)
; #define PG8_LDB(dst, b, h) do { _Pragma("unroll") for (int n = 0; n < 2; ++n) _Pragma("unroll") for (int k = 0; k < 2; ++k) dst[n][k] = *(const LAS bf16x8*)(lds + PG8_SB(b, h) + boff + n * 2048 + k * 1024); } while (0)
; #define PG8_WAIT_V(n) asm volatile("s_waitcnt vmcnt(" #n ")" ::: "memory")
; #define PG8_WAIT_L(n) asm volatile("s_waitcnt lgkmcnt(" #n ")" ::: "memory")
; #define PG8_BAR __builtin_amdgcn_s_barrier()
; #define PG8_SCHED __builtin_amdgcn_sched_barrier(0)
; template <class Epi, bool ALIGN_EPI>
; __device__ __forceinline__ void gemm_phase(LAS unsigned char* lds, const Gemm g, const StaticOrder& S, const Epi& E) {
;     ...
;         const char* nA = has_next ? (const char*)g.A + (size_t)nxt.pm * tstepA + (size_t)nxt.pn * g.a_pn_off * 2 + (size_t)(nxt.pm >> 4) * g.a_adj : cA; const char* nB = has_next ? (const char*)g.Bt + (size_t)nxt.pn * tstepB : cB;
;         for (int t = 0; t < nt; t += 2) {
;             const bool last = (t == nt - 2);
;             const char* a1 = cA + (size_t)(t + 1) * kstep;
;             const char* a2 = last ? nA : cA + (size_t)(t + 2) * kstep; const char* b2 = last ? nB : cB + (size_t)(t + 2) * kstep;
;             const char* a3 = a2 + kstep; const char* b3 = b2 + kstep;
;             PG8_LDB(B0, 0, 0); PG8_LDB(B1, 0, 1); PG8_SCHED; PG8_LDA(At, 0, 0); PG8_STAGE(PG8_SA(1, 1), a1 + hstepA, voffA);
;             PG8_WAIT_V(8); PG8_WAIT_L(0); PG8_BAR; PG8_MMA(0, 0, At, B0); PG8_MMA(0, 1, At, B1); PG8_BAR; PG8_SCHED;
;             PG8_LDA(At, 0, 1); PG8_STAGE(PG8_SB(0, 0), b2, voffB); PG8_STAGE(PG8_SB(0, 1), b2 + hstepB, voffB); PG8_STAGE(PG8_SA(0, 0), a2, voffA);
;             PG8_WAIT_V(8); PG8_WAIT_L(0); PG8_BAR; PG8_MMA(1, 0, At, B0); PG8_MMA(1, 1, At, B1); PG8_BAR; PG8_SCHED;
.LBB0_348:
	s_ashr_i32 s29, s28, 31
	s_lshl_b64 s[4:5], s[28:29], 19
	s_add_u32 s30, s18, s4
	s_addc_u32 s31, s19, s5
	s_and_b64 s[4:5], s[8:9], exec
	s_cselect_b32 s4, s31, s39
	s_cselect_b32 s5, s30, s38
	s_ashr_i32 s27, s26, 31
	s_lshl_b64 s[34:35], s[26:27], 19
	s_add_u32 s34, s14, s34
	s_addc_u32 s35, s15, s35
	s_and_b64 s[48:49], s[8:9], exec
	s_cselect_b32 s11, s35, s37
	s_cselect_b32 s27, s34, s36
	s_add_u32 s29, s36, 0x100
	s_addc_u32 s41, s37, 0
	s_add_u32 s36, s38, 0x40080
	s_addc_u32 s37, s39, 0
	s_mov_b32 s50, -2
	v_add_u32_e32 v0, 0x10000, v187
	ds_read_b128 v[34:37], v0
	ds_read_b128 v[54:57], v0 offset:1024
	ds_read_b128 v[74:77], v0 offset:2048
	ds_read_b128 v[94:97], v0 offset:3072
	v_add_u32_e32 v0, 0x14000, v187
	ds_read_b128 v[110:113], v0
	ds_read_b128 v[126:129], v0 offset:1024
	ds_read_b128 v[146:149], v0 offset:2048
	ds_read_b128 v[160:163], v0 offset:3072
	s_add_u32 s38, s36, 0xfffc0080
	s_addc_u32 s39, s37, -1
	s_cmp_eq_u32 s50, 12
	s_cselect_b32 s54, s5, s38
	s_cselect_b32 s55, s4, s39
	s_cselect_b32 s48, s27, s29
	s_cselect_b32 s49, s11, s41
	s_add_u32 s38, s54, 0x80
	s_addc_u32 s39, s55, 0
	ds_read_b128 v[164:167], v188
	ds_read_b128 v[168:171], v188 offset:1024
	ds_read_b128 v[172:175], v188 offset:2048
	ds_read_b128 v[176:179], v188 offset:3072
	ds_read_b128 v[190:193], v188 offset:4096
	ds_read_b128 v[202:205], v188 offset:5120
	ds_read_b128 v[206:209], v188 offset:6144
	ds_read_b128 v[210:213], v188 offset:7168
	s_mov_b32 m0, s91
	s_nop 0
	global_load_lds_dwordx4 v180, s[36:37]
	s_nop 0
	s_mov_b32 m0, s93
	s_nop 0
	global_load_lds_dwordx4 v182, s[36:37]
	s_waitcnt vmcnt(8)
	s_waitcnt lgkmcnt(0)
	s_setprio 1
	s_barrier
	v_mfma_f32_16x16x32_bf16 v[154:157], v[34:37], v[164:167], 0
	v_mfma_f32_16x16x32_bf16 v[154:157], v[54:57], v[168:171], v[154:157]
	v_mfma_f32_16x16x32_bf16 v[150:153], v[74:77], v[164:167], 0
	v_mfma_f32_16x16x32_bf16 v[150:153], v[94:97], v[168:171], v[150:153]
	v_mfma_f32_16x16x32_bf16 v[142:145], v[110:113], v[164:167], 0
	v_mfma_f32_16x16x32_bf16 v[142:145], v[126:129], v[168:171], v[142:145]
	v_mfma_f32_16x16x32_bf16 v[138:141], v[146:149], v[164:167], 0
	v_mfma_f32_16x16x32_bf16 v[138:141], v[160:163], v[168:171], v[138:141]
	v_mfma_f32_16x16x32_bf16 v[118:121], v[146:149], v[172:175], 0
	v_mfma_f32_16x16x32_bf16 v[118:121], v[160:163], v[176:179], v[118:121]
	v_mfma_f32_16x16x32_bf16 v[122:125], v[110:113], v[172:175], 0
	v_mfma_f32_16x16x32_bf16 v[122:125], v[126:129], v[176:179], v[122:125]
	v_mfma_f32_16x16x32_bf16 v[130:133], v[74:77], v[172:175], 0
	v_mfma_f32_16x16x32_bf16 v[130:133], v[94:97], v[176:179], v[130:133]
	v_mfma_f32_16x16x32_bf16 v[134:137], v[34:37], v[172:175], 0
	v_mfma_f32_16x16x32_bf16 v[134:137], v[54:57], v[176:179], v[134:137]
	v_mfma_f32_16x16x32_bf16 v[114:117], v[34:37], v[190:193], 0
	v_mfma_f32_16x16x32_bf16 v[114:117], v[54:57], v[202:205], v[114:117]
	v_mfma_f32_16x16x32_bf16 v[106:109], v[74:77], v[190:193], 0
	v_mfma_f32_16x16x32_bf16 v[106:109], v[94:97], v[202:205], v[106:109]
	v_mfma_f32_16x16x32_bf16 v[102:105], v[110:113], v[190:193], 0
	v_mfma_f32_16x16x32_bf16 v[102:105], v[126:129], v[202:205], v[102:105]
	v_mfma_f32_16x16x32_bf16 v[98:101], v[146:149], v[190:193], 0
	v_mfma_f32_16x16x32_bf16 v[98:101], v[160:163], v[202:205], v[98:101]
	v_mfma_f32_16x16x32_bf16 v[78:81], v[146:149], v[206:209], 0
	v_mfma_f32_16x16x32_bf16 v[78:81], v[160:163], v[210:213], v[78:81]
	v_mfma_f32_16x16x32_bf16 v[82:85], v[110:113], v[206:209], 0
	v_mfma_f32_16x16x32_bf16 v[82:85], v[126:129], v[210:213], v[82:85]
	v_mfma_f32_16x16x32_bf16 v[86:89], v[74:77], v[206:209], 0
	v_mfma_f32_16x16x32_bf16 v[86:89], v[94:97], v[210:213], v[86:89]
	v_mfma_f32_16x16x32_bf16 v[90:93], v[34:37], v[206:209], 0
	v_mfma_f32_16x16x32_bf16 v[90:93], v[54:57], v[210:213], v[90:93]
	s_barrier
	s_setprio 0
	ds_read_b128 v[164:167], v188 offset:16384
	ds_read_b128 v[168:171], v188 offset:17408
	ds_read_b128 v[172:175], v188 offset:18432
	ds_read_b128 v[176:179], v188 offset:19456
	ds_read_b128 v[190:193], v188 offset:20480
	ds_read_b128 v[202:205], v188 offset:21504
	ds_read_b128 v[206:209], v188 offset:22528
	ds_read_b128 v[210:213], v188 offset:23552
	s_mov_b32 m0, s43
	s_nop 0
	global_load_lds_dwordx4 v181, s[48:49]
	s_add_u32 s96, s48, 0x40000
	s_mov_b32 m0, s44
	s_nop 0
	global_load_lds_dwordx4 v183, s[48:49]
	s_addc_u32 s97, s49, 0
	s_mov_b32 m0, s45
	s_nop 0
	global_load_lds_dwordx4 v181, s[96:97]
	s_nop 0
	s_mov_b32 m0, s56
	s_nop 0
	global_load_lds_dwordx4 v183, s[96:97]
	s_nop 0
	s_mov_b32 m0, s42
	s_nop 0
	global_load_lds_dwordx4 v180, s[54:55]
	s_nop 0
	s_mov_b32 m0, s57
	s_nop 0
	global_load_lds_dwordx4 v182, s[54:55]
	s_waitcnt vmcnt(8)
	s_waitcnt lgkmcnt(0)
	s_setprio 1
	s_barrier
; #define PG8_STAGE(bufoff, gbase, voff) do { _Pragma("unroll") for (int _i = 0; _i < 2; ++_i) { \
;         const unsigned _m0 = ldsb + (unsigned)((bufoff) + _i * 8192); const char* _gb = (const char*)(gbase); \
;         asm volatile("s_mov_b32 m0, %0\n\ts_nop 0\n\tglobal_load_lds_dwordx4 %1, %2" :: "s"(_m0), "v"((voff)[_i]), "s"(_gb) : "m0", "memory"); } } while (0)
; #define PG8_LDA(dst, b, h) do { _Pragma("unroll") for (int m = 0; m < 4; ++m) _Pragma("unroll") for (int k = 0; k < 2; ++k) dst[m][k] = *(const LAS bf16x8*)(lds + PG8_SA(b, h) + aoff + m * 2048 + k * 1024); } while (0)
; #define PG8_LDB(dst, b, h) do { _Pragma("unroll") for (int n = 0; n < 2; ++n) _Pragma("unroll") for (int k = 0; k < 2; ++k) dst[n][k] = *(const LAS bf16x8*)(lds + PG8_SB(b, h) + boff + n * 2048 + k * 1024); } while (0)
; #define PG8_MMA(ai, bj, At, Bt) do { __builtin_amdgcn_s_setprio(1); _Pragma("unroll") for (int m = 0; m < 4; ++m) _Pragma("unroll") for (int n = 0; n < 2; ++n) _Pragma("unroll") for (int k = 0; k < 2; ++k) \
;         acc[ai][bj][m][n] = __builtin_amdgcn_mfma_f32_16x16x32_bf16(Bt[n][k], At[m][k], acc[ai][bj][m][n], 0, 0, 0); __builtin_amdgcn_s_setprio(0); } while (0)
; #define PG8_WAIT_V(n) asm volatile("s_waitcnt vmcnt(" #n ")" ::: "memory")
; #define PG8_WAIT_L(n) asm volatile("s_waitcnt lgkmcnt(" #n ")" ::: "memory")
; #define PG8_BAR __builtin_amdgcn_s_barrier()
; #define PG8_SCHED __builtin_amdgcn_sched_barrier(0)
; template <class Epi, bool ALIGN_EPI>
; __device__ __forceinline__ void gemm_phase(LAS unsigned char* lds, const Gemm g, const StaticOrder& S, const Epi& E) {
;     ...
;             PG8_WAIT_V(8); PG8_WAIT_L(0); PG8_BAR; PG8_MMA(1, 0, At, B0); PG8_MMA(1, 1, At, B1); PG8_BAR; PG8_SCHED;
;             PG8_LDB(B0, 1, 0); PG8_LDB(B1, 1, 1); PG8_SCHED; PG8_LDA(At, 1, 0); PG8_STAGE(PG8_SA(0, 1), a2 + hstepA, voffA);
;             PG8_WAIT_V(8); PG8_WAIT_L(0); PG8_BAR; PG8_MMA(0, 0, At, B0); PG8_MMA(0, 1, At, B1); PG8_BAR; PG8_SCHED;
	v_mfma_f32_16x16x32_bf16 v[70:73], v[34:37], v[164:167], 0
	v_mfma_f32_16x16x32_bf16 v[66:69], v[74:77], v[164:167], 0
	v_mfma_f32_16x16x32_bf16 v[50:53], v[34:37], v[172:175], 0
	v_mfma_f32_16x16x32_bf16 v[46:49], v[74:77], v[172:175], 0
	v_mfma_f32_16x16x32_bf16 v[30:33], v[34:37], v[190:193], 0
	v_mfma_f32_16x16x32_bf16 v[26:29], v[74:77], v[190:193], 0
	v_mfma_f32_16x16x32_bf16 v[14:17], v[34:37], v[206:209], 0
	v_mfma_f32_16x16x32_bf16 v[10:13], v[74:77], v[206:209], 0
	v_mfma_f32_16x16x32_bf16 v[70:73], v[54:57], v[168:171], v[70:73]
	v_mfma_f32_16x16x32_bf16 v[66:69], v[94:97], v[168:171], v[66:69]
	v_mfma_f32_16x16x32_bf16 v[50:53], v[54:57], v[176:179], v[50:53]
	v_mfma_f32_16x16x32_bf16 v[46:49], v[94:97], v[176:179], v[46:49]
	v_mfma_f32_16x16x32_bf16 v[30:33], v[54:57], v[202:205], v[30:33]
	v_mfma_f32_16x16x32_bf16 v[26:29], v[94:97], v[202:205], v[26:29]
	v_mfma_f32_16x16x32_bf16 v[14:17], v[54:57], v[210:213], v[14:17]
	v_mfma_f32_16x16x32_bf16 v[10:13], v[94:97], v[210:213], v[10:13]
	s_setprio 0
	s_setprio 1
	v_mfma_f32_16x16x32_bf16 v[42:45], v[110:113], v[172:175], 0
	v_mfma_f32_16x16x32_bf16 v[38:41], v[146:149], v[172:175], 0
	v_mfma_f32_16x16x32_bf16 v[22:25], v[110:113], v[190:193], 0
	v_mfma_f32_16x16x32_bf16 v[18:21], v[146:149], v[190:193], 0
	v_mfma_f32_16x16x32_bf16 v[6:9], v[110:113], v[206:209], 0
	v_mfma_f32_16x16x32_bf16 v[2:5], v[146:149], v[206:209], 0
	v_mfma_f32_16x16x32_bf16 v[34:37], v[110:113], v[164:167], 0
	v_mfma_f32_16x16x32_bf16 v[54:57], v[146:149], v[164:167], 0
	v_mfma_f32_16x16x32_bf16 v[42:45], v[126:129], v[176:179], v[42:45]
	v_mfma_f32_16x16x32_bf16 v[38:41], v[160:163], v[176:179], v[38:41]
	v_mfma_f32_16x16x32_bf16 v[22:25], v[126:129], v[202:205], v[22:25]
	v_mfma_f32_16x16x32_bf16 v[18:21], v[160:163], v[202:205], v[18:21]
	v_mfma_f32_16x16x32_bf16 v[6:9], v[126:129], v[210:213], v[6:9]
	v_mfma_f32_16x16x32_bf16 v[2:5], v[160:163], v[210:213], v[2:5]
	v_mfma_f32_16x16x32_bf16 v[34:37], v[126:129], v[168:171], v[34:37]
	v_mfma_f32_16x16x32_bf16 v[54:57], v[160:163], v[168:171], v[54:57]
	s_barrier
	s_setprio 0
	v_add_u32_e32 v0, 0x18000, v187
	ds_read_b128 v[58:61], v0
	ds_read_b128 v[62:65], v0 offset:1024
	ds_read_b128 v[74:77], v0 offset:2048
	ds_read_b128 v[94:97], v0 offset:3072
	v_add_u32_e32 v0, 0x1c000, v187
	ds_read_b128 v[110:113], v0
	ds_read_b128 v[126:129], v0 offset:1024
	ds_read_b128 v[146:149], v0 offset:2048
	ds_read_b128 v[160:163], v0 offset:3072
	ds_read_b128 v[164:167], v188 offset:32768
	ds_read_b128 v[168:171], v188 offset:33792
	ds_read_b128 v[172:175], v188 offset:34816
	ds_read_b128 v[176:179], v188 offset:35840
	ds_read_b128 v[190:193], v188 offset:36864
	ds_read_b128 v[202:205], v188 offset:37888
	ds_read_b128 v[206:209], v188 offset:38912
	ds_read_b128 v[210:213], v188 offset:39936
	s_add_u32 s54, s54, 0x40000
	s_addc_u32 s55, s55, 0
	s_mov_b32 m0, s58
	s_nop 0
	global_load_lds_dwordx4 v180, s[54:55]
	s_nop 0
	s_mov_b32 m0, s59
	s_nop 0
	global_load_lds_dwordx4 v182, s[54:55]
	s_waitcnt vmcnt(8)
	s_waitcnt lgkmcnt(0)
	s_setprio 1
	s_barrier
	v_mfma_f32_16x16x32_bf16 v[154:157], v[58:61], v[164:167], v[154:157]
	v_mfma_f32_16x16x32_bf16 v[154:157], v[62:65], v[168:171], v[154:157]
	v_mfma_f32_16x16x32_bf16 v[150:153], v[74:77], v[164:167], v[150:153]
	v_mfma_f32_16x16x32_bf16 v[150:153], v[94:97], v[168:171], v[150:153]
	v_mfma_f32_16x16x32_bf16 v[142:145], v[110:113], v[164:167], v[142:145]
	v_mfma_f32_16x16x32_bf16 v[142:145], v[126:129], v[168:171], v[142:145]
	v_mfma_f32_16x16x32_bf16 v[138:141], v[146:149], v[164:167], v[138:141]
	v_mfma_f32_16x16x32_bf16 v[138:141], v[160:163], v[168:171], v[138:141]
	v_mfma_f32_16x16x32_bf16 v[118:121], v[146:149], v[172:175], v[118:121]
	v_mfma_f32_16x16x32_bf16 v[118:121], v[160:163], v[176:179], v[118:121]
	v_mfma_f32_16x16x32_bf16 v[122:125], v[110:113], v[172:175], v[122:125]
	v_mfma_f32_16x16x32_bf16 v[122:125], v[126:129], v[176:179], v[122:125]
	v_mfma_f32_16x16x32_bf16 v[130:133], v[74:77], v[172:175], v[130:133]
	v_mfma_f32_16x16x32_bf16 v[130:133], v[94:97], v[176:179], v[130:133]
	v_mfma_f32_16x16x32_bf16 v[134:137], v[58:61], v[172:175], v[134:137]
	v_mfma_f32_16x16x32_bf16 v[134:137], v[62:65], v[176:179], v[134:137]
	v_mfma_f32_16x16x32_bf16 v[114:117], v[58:61], v[190:193], v[114:117]
	v_mfma_f32_16x16x32_bf16 v[114:117], v[62:65], v[202:205], v[114:117]
	v_mfma_f32_16x16x32_bf16 v[106:109], v[74:77], v[190:193], v[106:109]
	v_mfma_f32_16x16x32_bf16 v[106:109], v[94:97], v[202:205], v[106:109]
	v_mfma_f32_16x16x32_bf16 v[102:105], v[110:113], v[190:193], v[102:105]
	v_mfma_f32_16x16x32_bf16 v[102:105], v[126:129], v[202:205], v[102:105]
	v_mfma_f32_16x16x32_bf16 v[98:101], v[146:149], v[190:193], v[98:101]
	v_mfma_f32_16x16x32_bf16 v[98:101], v[160:163], v[202:205], v[98:101]
	v_mfma_f32_16x16x32_bf16 v[78:81], v[146:149], v[206:209], v[78:81]
	v_mfma_f32_16x16x32_bf16 v[78:81], v[160:163], v[210:213], v[78:81]
	v_mfma_f32_16x16x32_bf16 v[82:85], v[110:113], v[206:209], v[82:85]
	v_mfma_f32_16x16x32_bf16 v[82:85], v[126:129], v[210:213], v[82:85]
	v_mfma_f32_16x16x32_bf16 v[86:89], v[74:77], v[206:209], v[86:89]
	v_mfma_f32_16x16x32_bf16 v[86:89], v[94:97], v[210:213], v[86:89]
	v_mfma_f32_16x16x32_bf16 v[90:93], v[58:61], v[206:209], v[90:93]
	v_mfma_f32_16x16x32_bf16 v[90:93], v[62:65], v[210:213], v[90:93]
	s_barrier
; #define PG8_STAGE(bufoff, gbase, voff) do { _Pragma("unroll") for (int _i = 0; _i < 2; ++_i) { \
;         const unsigned _m0 = ldsb + (unsigned)((bufoff) + _i * 8192); const char* _gb = (const char*)(gbase); \
;         asm volatile("s_mov_b32 m0, %0\n\ts_nop 0\n\tglobal_load_lds_dwordx4 %1, %2" :: "s"(_m0), "v"((voff)[_i]), "s"(_gb) : "m0", "memory"); } } while (0)
; #define PG8_LDA(dst, b, h) do { _Pragma("unroll") for (int m = 0; m < 4; ++m) _Pragma("unroll") for (int k = 0; k < 2; ++k) dst[m][k] = *(const LAS bf16x8*)(lds + PG8_SA(b, h) + aoff + m * 2048 + k * 1024); } while (0)
; #define PG8_MMA(ai, bj, At, Bt) do { __builtin_amdgcn_s_setprio(1); _Pragma("unroll") for (int m = 0; m < 4; ++m) _Pragma("unroll") for (int n = 0; n < 2; ++n) _Pragma("unroll") for (int k = 0; k < 2; ++k) \
;         acc[ai][bj][m][n] = __builtin_amdgcn_mfma_f32_16x16x32_bf16(Bt[n][k], At[m][k], acc[ai][bj][m][n], 0, 0, 0); __builtin_amdgcn_s_setprio(0); } while (0)
; #define PG8_WAIT_V(n) asm volatile("s_waitcnt vmcnt(" #n ")" ::: "memory")
; #define PG8_WAIT_L(n) asm volatile("s_waitcnt lgkmcnt(" #n ")" ::: "memory")
; #define PG8_BAR __builtin_amdgcn_s_barrier()
; #define PG8_SCHED __builtin_amdgcn_sched_barrier(0)
; template <class Epi, bool ALIGN_EPI>
; __device__ __forceinline__ void gemm_phase(LAS unsigned char* lds, const Gemm g, const StaticOrder& S, const Epi& E) {
;     ...
;             PG8_LDA(At, 1, 1); PG8_STAGE(PG8_SB(1, 0), b3, voffB); PG8_STAGE(PG8_SB(1, 1), b3 + hstepB, voffB); PG8_STAGE(PG8_SA(1, 0), a3, voffA);
;             PG8_WAIT_V(8); PG8_WAIT_L(0); PG8_BAR; PG8_MMA(1, 0, At, B0); PG8_MMA(1, 1, At, B1); PG8_BAR; PG8_SCHED;
;         }
	s_setprio 0
	ds_read_b128 v[164:167], v188 offset:49152
	ds_read_b128 v[168:171], v188 offset:50176
	ds_read_b128 v[172:175], v188 offset:51200
	ds_read_b128 v[176:179], v188 offset:52224
	ds_read_b128 v[190:193], v188 offset:53248
	ds_read_b128 v[202:205], v188 offset:54272
	ds_read_b128 v[206:209], v188 offset:55296
	ds_read_b128 v[210:213], v188 offset:56320
	s_add_u32 s54, s48, 0x80
	s_addc_u32 s55, s49, 0
	s_mov_b32 m0, s17
	s_nop 0
	global_load_lds_dwordx4 v181, s[54:55]
	s_add_u32 s48, s48, 0x40080
	s_mov_b32 m0, s60
	s_nop 0
	global_load_lds_dwordx4 v183, s[54:55]
	s_addc_u32 s49, s49, 0
	s_mov_b32 m0, s89
	s_nop 0
	global_load_lds_dwordx4 v181, s[48:49]
	s_nop 0
	s_mov_b32 m0, s90
	s_nop 0
	global_load_lds_dwordx4 v183, s[48:49]
	s_nop 0
	s_mov_b32 m0, s61
	s_nop 0
	global_load_lds_dwordx4 v180, s[38:39]
	s_nop 0
	s_mov_b32 m0, s88
	s_nop 0
	global_load_lds_dwordx4 v182, s[38:39]
	s_waitcnt vmcnt(8)
	s_waitcnt lgkmcnt(0)
	s_setprio 1
	s_barrier
	v_mfma_f32_16x16x32_bf16 v[70:73], v[58:61], v[164:167], v[70:73]
	v_mfma_f32_16x16x32_bf16 v[66:69], v[74:77], v[164:167], v[66:69]
	v_mfma_f32_16x16x32_bf16 v[50:53], v[58:61], v[172:175], v[50:53]
	v_mfma_f32_16x16x32_bf16 v[46:49], v[74:77], v[172:175], v[46:49]
	v_mfma_f32_16x16x32_bf16 v[30:33], v[58:61], v[190:193], v[30:33]
	v_mfma_f32_16x16x32_bf16 v[26:29], v[74:77], v[190:193], v[26:29]
	v_mfma_f32_16x16x32_bf16 v[14:17], v[58:61], v[206:209], v[14:17]
	v_mfma_f32_16x16x32_bf16 v[10:13], v[74:77], v[206:209], v[10:13]
	v_mfma_f32_16x16x32_bf16 v[70:73], v[62:65], v[168:171], v[70:73]
	v_mfma_f32_16x16x32_bf16 v[66:69], v[94:97], v[168:171], v[66:69]
	v_mfma_f32_16x16x32_bf16 v[50:53], v[62:65], v[176:179], v[50:53]
	v_mfma_f32_16x16x32_bf16 v[46:49], v[94:97], v[176:179], v[46:49]
	v_mfma_f32_16x16x32_bf16 v[30:33], v[62:65], v[202:205], v[30:33]
	v_mfma_f32_16x16x32_bf16 v[26:29], v[94:97], v[202:205], v[26:29]
	v_mfma_f32_16x16x32_bf16 v[14:17], v[62:65], v[210:213], v[14:17]
	v_mfma_f32_16x16x32_bf16 v[10:13], v[94:97], v[210:213], v[10:13]
	s_setprio 0
	s_setprio 1
	v_mfma_f32_16x16x32_bf16 v[34:37], v[110:113], v[164:167], v[34:37]
	v_mfma_f32_16x16x32_bf16 v[62:65], v[126:129], v[168:171], v[34:37]
	v_mfma_f32_16x16x32_bf16 v[34:37], v[146:149], v[164:167], v[54:57]
	v_mfma_f32_16x16x32_bf16 v[58:61], v[160:163], v[168:171], v[34:37]
	v_mfma_f32_16x16x32_bf16 v[34:37], v[110:113], v[172:175], v[42:45]
	v_mfma_f32_16x16x32_bf16 v[42:45], v[126:129], v[176:179], v[34:37]
	v_mfma_f32_16x16x32_bf16 v[34:37], v[146:149], v[172:175], v[38:41]
	v_mfma_f32_16x16x32_bf16 v[22:25], v[110:113], v[190:193], v[22:25]
	v_mfma_f32_16x16x32_bf16 v[18:21], v[146:149], v[190:193], v[18:21]
	v_mfma_f32_16x16x32_bf16 v[6:9], v[110:113], v[206:209], v[6:9]
	v_mfma_f32_16x16x32_bf16 v[2:5], v[146:149], v[206:209], v[2:5]
	v_mfma_f32_16x16x32_bf16 v[38:41], v[160:163], v[176:179], v[34:37]
	v_mfma_f32_16x16x32_bf16 v[22:25], v[126:129], v[202:205], v[22:25]
	v_mfma_f32_16x16x32_bf16 v[18:21], v[160:163], v[202:205], v[18:21]
	v_mfma_f32_16x16x32_bf16 v[6:9], v[126:129], v[210:213], v[6:9]
	v_mfma_f32_16x16x32_bf16 v[2:5], v[160:163], v[210:213], v[2:5]
	s_barrier
	s_setprio 0
	s_add_i32 s50, s50, 2
	s_add_u32 s29, s29, 0x100
	s_addc_u32 s41, s41, 0
	s_add_u32 s36, s36, 0x100
	s_addc_u32 s37, s37, 0
	s_cmp_gt_u32 s50, 13
